# static priority raise for waves 4-7 inside the attention units (one s_setprio 1 per unit, reset at unit end)
# baseline (speedup 1.0000x reference)
; __device__ __forceinline__ void glds16(const void* gsrc, LAS unsigned char* dst_uniform) { __builtin_amdgcn_global_load_lds((const unsigned*)gsrc, (LAS unsigned*)dst_uniform, 16, 0, 0); }
; #define ATT_SYNC() do { asm volatile("s_waitcnt vmcnt(0) lgkmcnt(0)" ::: "memory"); __syncthreads(); } while (0)
; __device__ __forceinline__ void xattn_unit(LAS unsigned char* lds, const bf16_t* Qx, const bf16_t* KV, int li, int b, int h, int qb, bf16_t* XO, const int tid) {
;     ...
; #pragma unroll 4
;     for (int ii = 0; ii < 16; ++ii) { const int i = wid * 16 + ii, key = 2 * i + hi, c = r32 ^ (key & 15);
;         glds16(Kb + (size_t)key * 8192 + c * 8, lds + i * 1024); }
;     bf16x8 qf[16]; { const bf16_t* qp = Qx + tok * 1024 + h * 256 + hi * 8;
; #pragma unroll
;         for (int s = 0; s < 16; ++s) qf[s] = *(const bf16x8*)(qp + 16 * s); }
;     ATT_SYNC();
.LBB0_432:
	v_add_u32_e32 v1, -6, v0
	v_bitop3_b32 v1, v1, v203, 9 bitop3:0x6c
	v_lshlrev_b32_e32 v208, 4, v1
	v_lshl_add_u64 v[10:11], v[8:9], 0, s[18:19]
	s_add_i32 s26, s24, s25
	v_add_u32_e32 v1, -4, v0
	v_lshl_add_u64 v[10:11], v[10:11], 0, v[208:209]
	s_mov_b32 m0, s26
	v_bitop3_b32 v1, v1, v203, 11 bitop3:0x6c
	global_load_lds_dwordx4 v[10:11], off
	v_lshlrev_b32_e32 v208, 4, v1
	v_lshl_add_u64 v[10:11], v[6:7], 0, s[18:19]
	v_add_u32_e32 v1, -2, v0
	v_lshl_add_u64 v[10:11], v[10:11], 0, v[208:209]
	s_add_i32 m0, s26, 0x400
	v_bitop3_b32 v1, v1, v203, 13 bitop3:0x6c
	global_load_lds_dwordx4 v[10:11], off
	v_lshlrev_b32_e32 v208, 4, v1
	v_lshl_add_u64 v[10:11], v[4:5], 0, s[18:19]
	v_lshl_add_u64 v[10:11], v[10:11], 0, v[208:209]
	s_add_i32 m0, s26, 0x800
	v_bitop3_b32 v1, v0, v203, 15 bitop3:0x6c
	global_load_lds_dwordx4 v[10:11], off
	v_lshlrev_b32_e32 v208, 4, v1
	v_lshl_add_u64 v[10:11], v[2:3], 0, s[18:19]
	v_lshl_add_u64 v[10:11], v[10:11], 0, v[208:209]
	s_add_i32 m0, s26, 0xc00
	s_addk_i32 s25, 0x1000
	global_load_lds_dwordx4 v[10:11], off
	v_lshl_add_u64 v[2:3], v[2:3], 0, s[28:29]
	v_add_u32_e32 v0, 8, v0
	v_lshl_add_u64 v[4:5], v[4:5], 0, s[28:29]
	v_lshl_add_u64 v[6:7], v[6:7], 0, s[28:29]
	v_lshl_add_u64 v[8:9], v[8:9], 0, s[28:29]
	s_cmpk_eq_i32 s25, 0x4000
	s_cbranch_scc0 .LBB0_432
	s_lshl_b32 s25, s30, 8
	s_and_b32 s25, s25, 0xf00
	s_lshl_b64 s[0:1], s[0:1], 12
	v_or_b32_e32 v0, s25, v203
	s_ashr_i32 s37, s36, 31
	v_or_b32_e32 v0, s0, v0
	v_mov_b32_e32 v1, s1
	v_lshl_add_u64 v[0:1], v[0:1], 0, s[36:37]
	v_lshlrev_b64 v[200:201], 10, v[0:1]
	v_lshlrev_b64 v[0:1], 11, v[0:1]
	v_lshl_add_u64 v[0:1], s[8:9], 0, v[0:1]
	v_lshl_add_u64 v[0:1], s[12:13], 1, v[0:1]
	v_mov_b32_e32 v197, v209
	v_lshl_add_u64 v[0:1], v[0:1], 0, v[196:197]
	global_load_dwordx4 v[112:115], v[0:1], off
	global_load_dwordx4 v[184:187], v[0:1], off offset:32
	global_load_dwordx4 v[180:183], v[0:1], off offset:64
	global_load_dwordx4 v[176:179], v[0:1], off offset:96
	global_load_dwordx4 v[172:175], v[0:1], off offset:128
	global_load_dwordx4 v[168:171], v[0:1], off offset:160
	global_load_dwordx4 v[164:167], v[0:1], off offset:192
	global_load_dwordx4 v[160:163], v[0:1], off offset:224
	global_load_dwordx4 v[156:159], v[0:1], off offset:256
	global_load_dwordx4 v[152:155], v[0:1], off offset:288
	global_load_dwordx4 v[148:151], v[0:1], off offset:320
	global_load_dwordx4 v[144:147], v[0:1], off offset:352
	global_load_dwordx4 v[140:143], v[0:1], off offset:384
	global_load_dwordx4 v[136:139], v[0:1], off offset:416
	global_load_dwordx4 v[132:135], v[0:1], off offset:448
	global_load_dwordx4 v[128:131], v[0:1], off offset:480
	v_add_u32_e32 v32, v205, v206
	s_waitcnt vmcnt(0) lgkmcnt(0)
	s_waitcnt vmcnt(0) lgkmcnt(0)
	s_barrier
	v_readfirstlane_b32 s99, v202
	s_nop 3
	s_bitcmp1_b32 s99, 8
	s_cbranch_scc0 .Lxa_prio1
	s_setprio 1

; __device__ __forceinline__ v4i16_t vtr(lds_cptr p) { return __builtin_amdgcn_ds_read_tr16_b64_v4i16((LAS v4i16_t*)p); }
; #define ATT_SYNC() do { asm volatile("s_waitcnt vmcnt(0) lgkmcnt(0)" ::: "memory"); __syncthreads(); } while (0)
; __device__ __forceinline__ void xattn_unit(LAS unsigned char* lds, const bf16_t* Qx, const bf16_t* KV, int li, int b, int h, int qb, bf16_t* XO, const int tid) {
;     ...
; #pragma unroll 1
;     for (int d0 = 0; d0 < 8; ++d0) { f32x16 acc = {};
; #pragma unroll
;         for (int ks = 0; ks < 16; ++ks) { const v4i16_t lo = vtr(vb + d0 * 16384 + ks * 1024), hh = vtr(vb + d0 * 16384 + ks * 1024 + 512);
;             const bf16x8 vf = {lo[0], lo[1], lo[2], lo[3], hh[0], hh[1], hh[2], hh[3]};
;             acc = __builtin_amdgcn_mfma_f32_32x32x16_bf16(vf, pf[ks], acc, 0, 0, 0); }
;         const u32x4 none[2] = {}; store_ot<false>(acc, inv, orow + 32 * d0, hi, 0.f, 0.f, none); }
;     ATT_SYNC();
.LBB0_436:
	v_add_u32_e32 v83, s0, v250
	ds_read_b64_tr_b16 v[0:1], v83
	ds_read_b64_tr_b16 v[2:3], v83 offset:512
	ds_read_b64_tr_b16 v[84:85], v83 offset:1024
	ds_read_b64_tr_b16 v[86:87], v83 offset:1536
	s_addk_i32 s0, 0x4000
	s_cmp_lg_u32 s0, 0x20000
	s_waitcnt lgkmcnt(2)
	v_mfma_f32_32x32x16_bf16 v[0:15], v[0:3], v[16:19], 0
	s_waitcnt lgkmcnt(0)
	v_mfma_f32_32x32x16_bf16 v[0:15], v[84:87], v[20:23], v[0:15]
	ds_read_b64_tr_b16 v[84:85], v83 offset:2048
	ds_read_b64_tr_b16 v[86:87], v83 offset:2560
	s_waitcnt lgkmcnt(0)
	v_mfma_f32_32x32x16_bf16 v[0:15], v[84:87], v[24:27], v[0:15]
	ds_read_b64_tr_b16 v[84:85], v83 offset:3072
	ds_read_b64_tr_b16 v[86:87], v83 offset:3584
	s_waitcnt lgkmcnt(0)
	v_mfma_f32_32x32x16_bf16 v[0:15], v[84:87], v[28:31], v[0:15]
	ds_read_b64_tr_b16 v[84:85], v83 offset:4096
	ds_read_b64_tr_b16 v[86:87], v83 offset:4608
	s_waitcnt lgkmcnt(0)
	v_mfma_f32_32x32x16_bf16 v[0:15], v[84:87], v[32:35], v[0:15]
	ds_read_b64_tr_b16 v[84:85], v83 offset:5120
	ds_read_b64_tr_b16 v[86:87], v83 offset:5632
	s_waitcnt lgkmcnt(0)
	v_mfma_f32_32x32x16_bf16 v[0:15], v[84:87], v[36:39], v[0:15]
	ds_read_b64_tr_b16 v[84:85], v83 offset:6144
	ds_read_b64_tr_b16 v[86:87], v83 offset:6656
	s_waitcnt lgkmcnt(0)
	v_mfma_f32_32x32x16_bf16 v[0:15], v[84:87], v[40:43], v[0:15]
	ds_read_b64_tr_b16 v[84:85], v83 offset:7168
	ds_read_b64_tr_b16 v[86:87], v83 offset:7680
	s_waitcnt lgkmcnt(0)
	v_mfma_f32_32x32x16_bf16 v[0:15], v[84:87], v[44:47], v[0:15]
	ds_read_b64_tr_b16 v[84:85], v83 offset:8192
	ds_read_b64_tr_b16 v[86:87], v83 offset:8704
	s_waitcnt lgkmcnt(0)
	v_mfma_f32_32x32x16_bf16 v[0:15], v[84:87], v[48:51], v[0:15]
	ds_read_b64_tr_b16 v[84:85], v83 offset:9216
	ds_read_b64_tr_b16 v[86:87], v83 offset:9728
	s_waitcnt lgkmcnt(0)
	v_mfma_f32_32x32x16_bf16 v[0:15], v[84:87], v[52:55], v[0:15]
	ds_read_b64_tr_b16 v[84:85], v83 offset:10240
	ds_read_b64_tr_b16 v[86:87], v83 offset:10752
	s_waitcnt lgkmcnt(0)
	v_mfma_f32_32x32x16_bf16 v[0:15], v[84:87], v[56:59], v[0:15]
	ds_read_b64_tr_b16 v[84:85], v83 offset:11264
	ds_read_b64_tr_b16 v[86:87], v83 offset:11776
	s_waitcnt lgkmcnt(0)
	v_mfma_f32_32x32x16_bf16 v[0:15], v[84:87], v[60:63], v[0:15]
	ds_read_b64_tr_b16 v[84:85], v83 offset:12288
	ds_read_b64_tr_b16 v[86:87], v83 offset:12800
	s_waitcnt lgkmcnt(0)
	v_mfma_f32_32x32x16_bf16 v[0:15], v[84:87], v[64:67], v[0:15]
	ds_read_b64_tr_b16 v[84:85], v83 offset:13312
	ds_read_b64_tr_b16 v[86:87], v83 offset:13824
	s_waitcnt lgkmcnt(0)
	v_mfma_f32_32x32x16_bf16 v[0:15], v[84:87], v[68:71], v[0:15]
	ds_read_b64_tr_b16 v[84:85], v83 offset:14336
	ds_read_b64_tr_b16 v[86:87], v83 offset:14848
	s_waitcnt lgkmcnt(0)
	v_mfma_f32_32x32x16_bf16 v[0:15], v[84:87], v[72:75], v[0:15]
	ds_read_b64_tr_b16 v[84:85], v83 offset:15360
	ds_read_b64_tr_b16 v[86:87], v83 offset:15872
	s_waitcnt lgkmcnt(0)
	v_mfma_f32_32x32x16_bf16 v[0:15], v[84:87], v[76:79], v[0:15]
	s_nop 11
	v_mul_f32_e32 v0, v82, v0
	v_mul_f32_e32 v1, v82, v1
	v_cvt_pk_bf16_f32 v0, v0, v1
	v_mul_f32_e32 v1, v82, v2
	v_mul_f32_e32 v2, v82, v3
	v_cvt_pk_bf16_f32 v1, v1, v2
	v_mul_f32_e32 v2, v82, v4
	v_mul_f32_e32 v3, v82, v5
	v_cvt_pk_bf16_f32 v2, v2, v3
	v_mul_f32_e32 v3, v82, v6
	v_mul_f32_e32 v4, v82, v7
	v_cvt_pk_bf16_f32 v3, v3, v4
	v_mul_f32_e32 v4, v82, v8
	v_mul_f32_e32 v5, v82, v9
	v_cvt_pk_bf16_f32 v4, v4, v5
	v_mul_f32_e32 v5, v82, v10
	v_mul_f32_e32 v6, v82, v11
	v_cvt_pk_bf16_f32 v5, v5, v6
	v_mul_f32_e32 v6, v82, v12
	v_mul_f32_e32 v7, v82, v13
	v_cvt_pk_bf16_f32 v6, v6, v7
	v_mul_f32_e32 v7, v82, v14
	v_mul_f32_e32 v8, v82, v15
	v_cvt_pk_bf16_f32 v7, v7, v8
	v_permlane32_swap_b32_e32 v0, v2
	v_permlane32_swap_b32_e32 v1, v3
	v_permlane32_swap_b32_e32 v4, v6
	v_permlane32_swap_b32_e32 v5, v7
	global_store_dwordx4 v[80:81], v[0:3], off
	global_store_dwordx4 v[80:81], v[4:7], off offset:32
	v_lshl_add_u64 v[80:81], v[80:81], 0, 64
	s_cbranch_scc1 .LBB0_436
	s_waitcnt vmcnt(0) lgkmcnt(0)
	s_add_i32 s16, s16, 1
	s_mov_b64 s[0:1], 0
	s_setprio 0
	s_barrier
	s_branch .LBB0_427

; #define ATT_SYNC() do { asm volatile("s_waitcnt vmcnt(0) lgkmcnt(0)" ::: "memory"); __syncthreads(); } while (0)
; __device__ __forceinline__ void dil_unit(LAS unsigned char* lds, const LAS float* btab, const bf16_t* QKV, int gi, int ldil, int b, int h, int r, int ub, bf16_t* AO, float* lseacc, const int tid) {
;     ...
;     if (hi == 0) *lp = ln;
;     ATT_SYNC();
; __global__ void __launch_bounds__(NWAVES * 64, 2) mk_fwd(Args a) {
;     ...
;             for (int u = vcu; u < 512; u += G) { const int x = u & 15, bh = u >> 4, h = bh & 7;
.LBB0_657:
	s_or_b64 exec, exec, s[0:1]
	s_setprio 0
	s_waitcnt lgkmcnt(0)
	v_readlane_b32 s0, v253, 63
	s_add_i32 s19, s19, s0
	s_cmpk_gt_i32 s19, 0x1ff
	s_barrier
	v_readlane_b32 s1, v254, 0
	s_cbranch_scc1 .LBB0_689

; #define LAS __attribute__((address_space(3)))
; __device__ __forceinline__ void glds16(const void* gsrc, LAS unsigned char* dst_uniform) { __builtin_amdgcn_global_load_lds((const unsigned*)gsrc, (LAS unsigned*)dst_uniform, 16, 0, 0); }
; #define ATT_SYNC() do { asm volatile("s_waitcnt vmcnt(0) lgkmcnt(0)" ::: "memory"); __syncthreads(); } while (0)
; __device__ __forceinline__ void dil_unit(LAS unsigned char* lds, const LAS float* btab, const bf16_t* QKV, int gi, int ldil, int b, int h, int r, int ub, bf16_t* AO, float* lseacc, const int tid) {
;     ...
;     for (int t = 0; t < 5; ++t) { f32x16 acc = {}; const lds_cptr kp = (lds_cptr)lds + (32 * wid + 32 * t + r32) * 256;
; #pragma unroll
;         for (int s = 0; s < 8; ++s) { const bf16x8 kf = *(const LAS bf16x8*)(kp + (((2 * s + hi) ^ r15) << 4)); acc = __builtin_amdgcn_mfma_f32_32x32x16_bf16(kf, qf[s], acc, 0, 0, 0); }
;         S[t] = acc; }
;     ATT_SYNC();
; #pragma unroll 1
;     for (int ii = 0; ii < 12; ++ii) { const int i = wid * 12 + ii, d0 = i / 24, ks = i % 24, kk = 16 * ks + 8 * hi + ((lane >> 2) & 7), cc = lane & 3; int ki = k0 + kk; ki = ki < 0 ? 0 : (ki >= sub_len ? sub_len - 1 : ki);
;         glds16(base + (tokb + ((size_t)ki << ldil)) * 3072 + 2048 + 32 * d0 + 8 * cc, lds + i * 1024); }
;     float m = -3.0e38f;
; #pragma unroll
;     for (int t = 0; t < 5; ++t)
; #pragma unroll
;         for (int rr = 0; rr < 16; ++rr) { const int cr = (rr & 3) + 8 * (rr >> 2) + 4 * hi, jk = 32 * t + cr - r32, ki = k0 + 32 * wid + 32 * t + cr;
;             float s = S[t][rr] + btab[jk + 32];
;             s = ((unsigned)ki < (unsigned)sub_len) ? s : -1e30f;
;             S[t][rr] = s; m = fmaxf(m, s); }
.LBB0_665:
	s_mul_i32 s30, s20, 12
	s_add_i32 s30, s30, s29
	s_mul_hi_i32 s31, s30, 0x2aaaaaab
	s_lshr_b32 s35, s31, 31
	s_ashr_i32 s31, s31, 2
	s_add_i32 s35, s31, s35
	s_mul_i32 s31, s35, 24
	s_sub_i32 s30, s30, s31
	v_lshl_add_u32 v65, s30, 4, v64
	v_min_i32_e32 v66, s18, v65
	v_cmp_lt_i32_e32 vcc, -1, v65
	v_mov_b64_e32 v[68:69], s[2:3]
	v_lshlrev_b32_e32 v208, 1, v212
	v_cndmask_b32_e32 v66, 0, v66, vcc
	v_ashrrev_i32_e32 v67, 31, v66
	v_lshlrev_b64 v[66:67], s12, v[66:67]
	v_lshl_add_u64 v[66:67], v[66:67], 0, s[0:1]
	v_mad_u64_u32 v[68:69], s[30:31], v66, s36, v[68:69]
	v_mov_b32_e32 v66, v69
	v_mad_u64_u32 v[66:67], s[30:31], v67, s36, v[66:67]
	s_lshl_b32 s30, s35, 5
	v_mov_b32_e32 v69, v66
	s_ashr_i32 s31, s30, 31
	v_lshl_add_u64 v[66:67], s[30:31], 1, v[68:69]
	v_lshl_add_u64 v[66:67], v[66:67], 0, v[208:209]
	s_mov_b64 s[30:31], 0x1000
	v_lshl_add_u64 v[66:67], v[66:67], 0, s[30:31]
	s_mov_b32 m0, s26
	s_add_i32 s29, s29, 1
	global_load_lds_dwordx4 v[66:67], off
	s_addk_i32 s26, 0x400
	s_cmp_eq_u32 s29, 12
	s_cbranch_scc0 .LBB0_665
	v_readfirstlane_b32 s99, v237
	s_nop 3
	s_bitcmp1_b32 s99, 8
	s_cbranch_scc0 .Ldil_prio1
	s_setprio 1
.Ldil_prio1:
	v_lshlrev_b64 v[242:243], 5, v[218:219]
	s_lshl_b32 s96, s21, 2
	v_lshl_add_u64 v[242:243], s[8:9], 0, v[242:243]
	s_nop 0
	v_lshl_add_u64 v[242:243], v[242:243], 0, s[96:97]
	s_nop 0
	global_load_dword v241, v[242:243], off
	v_mfma_f32_32x32x16_bf16 v[64:79], v[48:51], v[0:3], 0
	s_add_i32 s0, 0, 0x20000
	s_add_i32 s1, s28, s27
	s_mov_b32 s2, 0xff61b1e6
	s_lshl_b32 s96, s24, 1
	v_mfma_f32_32x32x16_bf16 v[64:79], v[24:27], v[80:83], v[64:79]
	v_mfma_f32_32x32x16_bf16 v[64:79], v[52:55], v[84:87], v[64:79]
	v_mfma_f32_32x32x16_bf16 v[64:79], v[32:35], v[88:91], v[64:79]
	v_mfma_f32_32x32x16_bf16 v[64:79], v[56:59], v[92:95], v[64:79]
	v_mfma_f32_32x32x16_bf16 v[64:79], v[36:39], v[96:99], v[64:79]
	v_mfma_f32_32x32x16_bf16 v[64:79], v[60:63], v[100:103], v[64:79]
	v_mfma_f32_32x32x16_bf16 v[48:63], v[44:47], v[0:3], 0
	v_mfma_f32_32x32x16_bf16 v[48:63], v[4:7], v[80:83], v[48:63]
	v_mfma_f32_32x32x16_bf16 v[48:63], v[128:131], v[84:87], v[48:63]
	v_mfma_f32_32x32x16_bf16 v[48:63], v[8:11], v[88:91], v[48:63]
	v_mfma_f32_32x32x16_bf16 v[48:63], v[136:139], v[92:95], v[48:63]
	v_mfma_f32_32x32x16_bf16 v[64:79], v[40:43], v[104:107], v[64:79]
	v_mfma_f32_32x32x16_bf16 v[48:63], v[12:15], v[96:99], v[48:63]
	v_mfma_f32_32x32x16_bf16 v[32:47], v[20:23], v[0:3], 0
	v_mfma_f32_32x32x16_bf16 v[48:63], v[144:147], v[100:103], v[48:63]
	v_mfma_f32_32x32x16_bf16 v[32:47], v[148:151], v[80:83], v[32:47]
	v_mfma_f32_32x32x16_bf16 v[48:63], v[16:19], v[104:107], v[48:63]
	v_mfma_f32_32x32x16_bf16 v[32:47], v[28:31], v[84:87], v[32:47]
	v_mfma_f32_32x32x16_bf16 v[16:31], v[192:195], v[0:3], 0
	v_mfma_f32_32x32x16_bf16 v[0:15], v[140:143], v[0:3], 0
	v_mfma_f32_32x32x16_bf16 v[16:31], v[116:119], v[80:83], v[16:31]
	v_mfma_f32_32x32x16_bf16 v[0:15], v[152:155], v[80:83], v[0:15]
	v_lshlrev_b32_e32 v80, 2, v240
	v_add_u32_e32 v83, s0, v220
	v_lshlrev_b32_e32 v82, 2, v239
	v_mfma_f32_32x32x16_bf16 v[16:31], v[196:199], v[84:87], v[16:31]
	v_mfma_f32_32x32x16_bf16 v[0:15], v[156:159], v[84:87], v[0:15]
	v_or_b32_e32 v84, s1, v82
	v_or_b32_e32 v85, 1, v82
	v_cmp_gt_u32_e32 vcc, s17, v84
	v_or_b32_e32 v86, 2, v82
	v_or_b32_e32 v87, s1, v86
	v_mfma_f32_32x32x16_bf16 v[32:47], v[160:163], v[88:91], v[32:47]
	v_mfma_f32_32x32x16_bf16 v[16:31], v[120:123], v[88:91], v[16:31]
	v_mfma_f32_32x32x16_bf16 v[0:15], v[164:167], v[88:91], v[0:15]
	v_or_b32_e32 v91, 8, v82
	v_or_b32_e32 v90, 16, v82
	v_mfma_f32_32x32x16_bf16 v[32:47], v[108:111], v[92:95], v[32:47]
	v_mfma_f32_32x32x16_bf16 v[16:31], v[200:203], v[92:95], v[16:31]
	v_mfma_f32_32x32x16_bf16 v[0:15], v[172:175], v[92:95], v[0:15]
	v_or_b32_e32 v92, 10, v82
	v_mfma_f32_32x32x16_bf16 v[32:47], v[168:171], v[96:99], v[32:47]
	v_mfma_f32_32x32x16_bf16 v[16:31], v[124:127], v[96:99], v[16:31]
	v_mfma_f32_32x32x16_bf16 v[0:15], v[180:183], v[96:99], v[0:15]
	v_sub_u32_e32 v98, v83, v80
	ds_read2_b32 v[80:81], v98 offset0:32 offset1:33
	ds_read2_b32 v[94:95], v98 offset0:50 offset1:51
	s_waitcnt lgkmcnt(0)
	v_add_f32_e32 v64, v64, v80
	v_or_b32_e32 v80, s1, v85
	v_cndmask_b32_e32 v64, v231, v64, vcc
	v_add_f32_e32 v65, v65, v81
	v_cmp_gt_u32_e32 vcc, s17, v80
	ds_read2_b32 v[80:81], v98 offset0:34 offset1:35
	v_add_f32_e32 v74, v74, v94
	v_cndmask_b32_e32 v65, v231, v65, vcc
	v_cmp_gt_u32_e32 vcc, s17, v87
	v_or_b32_e32 v87, 3, v82
	s_waitcnt lgkmcnt(0)
	v_add_f32_e32 v66, v66, v80
	v_or_b32_e32 v80, s1, v87
	v_cndmask_b32_e32 v66, v231, v66, vcc
	v_add_f32_e32 v67, v67, v81
	v_cmp_gt_u32_e32 vcc, s17, v80
	ds_read2_b32 v[80:81], v98 offset0:40 offset1:41
	v_max3_f32 v84, v64, s2, v65
	v_cndmask_b32_e32 v67, v231, v67, vcc
	v_max3_f32 v88, v84, v66, v67
	v_or_b32_e32 v84, s1, v91
	v_cmp_gt_u32_e32 vcc, s17, v84
	v_or_b32_e32 v84, 9, v82
	s_waitcnt lgkmcnt(0)
	v_add_f32_e32 v68, v68, v80
	v_or_b32_e32 v80, s1, v84
	v_cndmask_b32_e32 v68, v231, v68, vcc
	v_add_f32_e32 v69, v69, v81
	v_cmp_gt_u32_e32 vcc, s17, v80
	v_or_b32_e32 v81, s1, v92
	v_add_f32_e32 v75, v75, v95
	v_cndmask_b32_e32 v69, v231, v69, vcc
	v_max3_f32 v80, v88, v68, v69
	ds_read2_b32 v[88:89], v98 offset0:42 offset1:43
	v_cmp_gt_u32_e32 vcc, s17, v81
	v_or_b32_e32 v81, 11, v82
	v_or_b32_e32 v94, 24, v82
	v_or_b32_e32 v95, 25, v82
	s_waitcnt lgkmcnt(0)
	v_add_f32_e32 v70, v70, v88
	v_or_b32_e32 v88, s1, v81
	v_cndmask_b32_e32 v70, v231, v70, vcc
	v_add_f32_e32 v71, v71, v89
	v_cmp_gt_u32_e32 vcc, s17, v88
	ds_read2_b32 v[88:89], v98 offset0:48 offset1:49
	v_mfma_f32_32x32x16_bf16 v[32:47], v[112:115], v[100:103], v[32:47]
	v_cndmask_b32_e32 v71, v231, v71, vcc
	v_max3_f32 v93, v80, v70, v71
	v_or_b32_e32 v80, s1, v90
	s_waitcnt lgkmcnt(0)
; __device__ __forceinline__ void dil_unit(LAS unsigned char* lds, const LAS float* btab, const bf16_t* QKV, int gi, int ldil, int b, int h, int r, int ub, bf16_t* AO, float* lseacc, const int tid) {
;     ...
; #pragma unroll
;     for (int t = 0; t < 5; ++t)
; #pragma unroll
;         for (int rr = 0; rr < 16; ++rr) { const int cr = (rr & 3) + 8 * (rr >> 2) + 4 * hi, jk = 32 * t + cr - r32, ki = k0 + 32 * wid + 32 * t + cr;
;             float s = S[t][rr] + btab[jk + 32];
;             s = ((unsigned)ki < (unsigned)sub_len) ? s : -1e30f;
;             S[t][rr] = s; m = fmaxf(m, s); }
	v_add_f32_e32 v72, v72, v88
	v_cmp_gt_u32_e32 vcc, s17, v80
	v_or_b32_e32 v88, 17, v82
	v_add_f32_e32 v73, v73, v89
	v_cndmask_b32_e32 v80, v231, v72, vcc
	v_or_b32_e32 v72, s1, v88
	v_cmp_gt_u32_e32 vcc, s17, v72
	v_or_b32_e32 v89, 18, v82
	v_mfma_f32_32x32x16_bf16 v[16:31], v[204:207], v[100:103], v[16:31]
	v_cndmask_b32_e32 v72, v231, v73, vcc
	v_max3_f32 v96, v93, v80, v72
	v_or_b32_e32 v73, s1, v89
	v_or_b32_e32 v93, 19, v82
	v_cmp_gt_u32_e32 vcc, s17, v73
	v_or_b32_e32 v73, s1, v93
	s_add_i32 s2, s1, 32
	v_cndmask_b32_e32 v74, v231, v74, vcc
	v_cmp_gt_u32_e32 vcc, s17, v73
	v_mfma_f32_32x32x16_bf16 v[0:15], v[184:187], v[100:103], v[0:15]
	s_nop 0
	v_cndmask_b32_e32 v73, v231, v75, vcc
	v_max3_f32 v99, v96, v74, v73
	ds_read2_b32 v[96:97], v98 offset0:56 offset1:57
	v_or_b32_e32 v75, s1, v94
	v_cmp_gt_u32_e32 vcc, s17, v75
	v_or_b32_e32 v75, s1, v95
	v_mfma_f32_32x32x16_bf16 v[32:47], v[176:179], v[104:107], v[32:47]
	s_waitcnt lgkmcnt(0)
	v_add_f32_e32 v76, v76, v96
	v_cndmask_b32_e32 v76, v231, v76, vcc
	v_add_f32_e32 v77, v77, v97
	v_cmp_gt_u32_e32 vcc, s17, v75
	v_or_b32_e32 v96, 26, v82
	v_or_b32_e32 v97, 27, v82
	v_cndmask_b32_e32 v75, v231, v77, vcc
	v_max3_f32 v100, v99, v76, v75
	ds_read2_b32 v[98:99], v98 offset0:58 offset1:59
	v_or_b32_e32 v77, s1, v96
	v_cmp_gt_u32_e32 vcc, s17, v77
	v_mfma_f32_32x32x16_bf16 v[16:31], v[132:135], v[104:107], v[16:31]
	s_waitcnt lgkmcnt(0)
	v_add_f32_e32 v78, v78, v98
	v_sub_u32_e32 v98, 32, v240
	v_lshlrev_b32_e32 v101, 2, v98
	v_add_u32_e32 v98, v83, v101
	v_add_f32_e32 v79, v79, v99
	ds_read2_b32 v[98:99], v98 offset0:32 offset1:33
	v_cndmask_b32_e32 v77, v231, v78, vcc
	v_or_b32_e32 v78, s1, v97
	v_cmp_gt_u32_e32 vcc, s17, v78
	v_add3_u32 v102, s0, v101, v220
	s_waitcnt lgkmcnt(0)
	v_add_f32_e32 v48, v48, v98
	v_cndmask_b32_e32 v78, v231, v79, vcc
	v_max3_f32 v79, v100, v77, v78
	v_or_b32_e32 v100, s2, v82
	v_cmp_gt_u32_e32 vcc, s17, v100
	v_or_b32_e32 v98, s2, v85
	v_add_f32_e32 v49, v49, v99
	v_cndmask_b32_e32 v48, v231, v48, vcc
	v_cmp_gt_u32_e32 vcc, s17, v98
	ds_read2_b32 v[98:99], v102 offset0:34 offset1:35
	v_mfma_f32_32x32x16_bf16 v[0:15], v[188:191], v[104:107], v[0:15]
	v_cndmask_b32_e32 v49, v231, v49, vcc
	v_max3_f32 v100, v79, v48, v49
	v_or_b32_e32 v79, s2, v86
	s_waitcnt lgkmcnt(0)
	v_add_f32_e32 v50, v50, v98
	v_add_f32_e32 v51, v51, v99
	ds_read2_b32 v[98:99], v102 offset0:40 offset1:41
	v_cmp_gt_u32_e32 vcc, s17, v79
	s_waitcnt lgkmcnt(0)
	v_add_f32_e32 v52, v52, v98
	v_cndmask_b32_e32 v79, v231, v50, vcc
	v_or_b32_e32 v50, s2, v87
	v_cmp_gt_u32_e32 vcc, s17, v50
	v_add_f32_e32 v53, v53, v99
	ds_read2_b32 v[98:99], v102 offset0:42 offset1:43
	v_cndmask_b32_e32 v50, v231, v51, vcc
	v_or_b32_e32 v51, s2, v91
	v_cmp_gt_u32_e32 vcc, s17, v51
	v_or_b32_e32 v51, s2, v84
	v_max3_f32 v100, v100, v79, v50
	v_cndmask_b32_e32 v52, v231, v52, vcc
	v_cmp_gt_u32_e32 vcc, s17, v51
	s_nop 1
	v_cndmask_b32_e32 v51, v231, v53, vcc
	v_max3_f32 v53, v100, v52, v51
	v_or_b32_e32 v100, s2, v92
	v_cmp_gt_u32_e32 vcc, s17, v100
	ds_read2_b32 v[100:101], v102 offset0:48 offset1:49
	s_waitcnt lgkmcnt(0)
	v_add_f32_e32 v54, v54, v98
	v_cndmask_b32_e32 v98, v231, v54, vcc
	v_or_b32_e32 v54, s2, v81
	v_cmp_gt_u32_e32 vcc, s17, v54
	v_add_f32_e32 v54, v56, v100
	v_add_f32_e32 v56, v57, v101
	ds_read2_b32 v[100:101], v102 offset0:50 offset1:51
	v_add_f32_e32 v55, v55, v99
	v_cndmask_b32_e32 v55, v231, v55, vcc
	v_max3_f32 v99, v53, v98, v55
	v_or_b32_e32 v53, s2, v90
	v_cmp_gt_u32_e32 vcc, s17, v53
	v_or_b32_e32 v53, s2, v88
	s_waitcnt lgkmcnt(0)
	v_add_f32_e32 v57, v58, v100
	v_cndmask_b32_e32 v54, v231, v54, vcc
	v_cmp_gt_u32_e32 vcc, s17, v53
	v_add_f32_e32 v58, v59, v101
	ds_read2_b32 v[100:101], v102 offset0:56 offset1:57
	v_cndmask_b32_e32 v53, v231, v56, vcc
	v_or_b32_e32 v56, s2, v89
	v_cmp_gt_u32_e32 vcc, s17, v56
	v_or_b32_e32 v56, s2, v93
	s_waitcnt lgkmcnt(0)
	v_add_f32_e32 v59, v60, v100
	v_cndmask_b32_e32 v57, v231, v57, vcc
	v_cmp_gt_u32_e32 vcc, s17, v56
	v_add_f32_e32 v60, v61, v101
	v_or_b32_e32 v100, s2, v96
	v_cndmask_b32_e32 v56, v231, v58, vcc
	v_or_b32_e32 v58, s2, v94
	v_cmp_gt_u32_e32 vcc, s17, v58
	v_or_b32_e32 v58, s2, v95
	v_max3_f32 v99, v99, v54, v53
	v_cndmask_b32_e32 v59, v231, v59, vcc
	v_cmp_gt_u32_e32 vcc, s17, v58
	v_max3_f32 v99, v99, v57, v56
	s_nop 0
	v_cndmask_b32_e32 v58, v231, v60, vcc
	ds_read2_b32 v[60:61], v102 offset0:58 offset1:59
	v_cmp_gt_u32_e32 vcc, s17, v100
	v_or_b32_e32 v100, s25, v82
	v_max3_f32 v99, v99, v59, v58
	s_waitcnt lgkmcnt(0)
	v_add_f32_e32 v60, v62, v60
	v_or_b32_e32 v62, s2, v97
	v_cndmask_b32_e32 v60, v231, v60, vcc
	v_cmp_gt_u32_e32 vcc, s17, v62
	v_sub_u32_e32 v62, 64, v240
	v_lshlrev_b32_e32 v101, 2, v62
	v_add_u32_e32 v62, v83, v101
	v_add_f32_e32 v61, v63, v61
	ds_read2_b32 v[62:63], v62 offset0:32 offset1:33
	v_cndmask_b32_e32 v61, v231, v61, vcc
	v_cmp_gt_u32_e32 vcc, s17, v100
	v_add3_u32 v102, s0, v101, v220
	v_or_b32_e32 v100, s25, v86
	s_waitcnt lgkmcnt(0)
	v_add_f32_e32 v32, v32, v62
	v_or_b32_e32 v62, s25, v85
	v_cndmask_b32_e32 v32, v231, v32, vcc
	v_add_f32_e32 v33, v33, v63
	v_cmp_gt_u32_e32 vcc, s17, v62
	ds_read2_b32 v[62:63], v102 offset0:34 offset1:35
	v_max3_f32 v99, v99, v60, v61
	v_cndmask_b32_e32 v33, v231, v33, vcc
	v_cmp_gt_u32_e32 vcc, s17, v100
	ds_read2_b32 v[100:101], v102 offset0:40 offset1:41
	s_waitcnt lgkmcnt(0)
	v_add_f32_e32 v34, v34, v62
	v_cndmask_b32_e32 v62, v231, v34, vcc
	v_or_b32_e32 v34, s25, v87
	v_add_f32_e32 v35, v35, v63
	v_add_f32_e32 v36, v36, v100
	v_add_f32_e32 v37, v37, v101
	ds_read2_b32 v[100:101], v102 offset0:42 offset1:43
	v_cmp_gt_u32_e32 vcc, s17, v34
	v_max3_f32 v99, v99, v32, v33
	s_add_i32 s2, s1, 0x60
	v_cndmask_b32_e32 v34, v231, v35, vcc
	v_or_b32_e32 v35, s25, v91
	v_cmp_gt_u32_e32 vcc, s17, v35
	v_or_b32_e32 v35, s25, v84
	s_waitcnt lgkmcnt(0)
; __device__ __forceinline__ void dil_unit(LAS unsigned char* lds, const LAS float* btab, const bf16_t* QKV, int gi, int ldil, int b, int h, int r, int ub, bf16_t* AO, float* lseacc, const int tid) {
;     ...
; #pragma unroll
;     for (int t = 0; t < 5; ++t)
; #pragma unroll
;         for (int rr = 0; rr < 16; ++rr) { const int cr = (rr & 3) + 8 * (rr >> 2) + 4 * hi, jk = 32 * t + cr - r32, ki = k0 + 32 * wid + 32 * t + cr;
;             float s = S[t][rr] + btab[jk + 32];
;             s = ((unsigned)ki < (unsigned)sub_len) ? s : -1e30f;
;             S[t][rr] = s; m = fmaxf(m, s); }
	v_add_f32_e32 v38, v38, v100
	v_cndmask_b32_e32 v36, v231, v36, vcc
	v_cmp_gt_u32_e32 vcc, s17, v35
	v_add_f32_e32 v39, v39, v101
	ds_read2_b32 v[100:101], v102 offset0:48 offset1:49
	v_max3_f32 v63, v99, v62, v34
	v_cndmask_b32_e32 v35, v231, v37, vcc
	v_max3_f32 v37, v63, v36, v35
	v_or_b32_e32 v63, s25, v92
	v_cmp_gt_u32_e32 vcc, s17, v63
	s_addk_i32 s1, 0x80
	s_nop 0
	v_cndmask_b32_e32 v63, v231, v38, vcc
	v_or_b32_e32 v38, s25, v81
	v_cmp_gt_u32_e32 vcc, s17, v38
	s_waitcnt lgkmcnt(0)
	v_add_f32_e32 v38, v40, v100
	v_add_f32_e32 v40, v41, v101
	ds_read2_b32 v[100:101], v102 offset0:50 offset1:51
	v_cndmask_b32_e32 v39, v231, v39, vcc
	v_max3_f32 v99, v37, v63, v39
	v_or_b32_e32 v37, s25, v90
	v_cmp_gt_u32_e32 vcc, s17, v37
	s_waitcnt lgkmcnt(0)
	v_add_f32_e32 v41, v42, v100
	v_add_f32_e32 v42, v43, v101
	ds_read2_b32 v[100:101], v102 offset0:56 offset1:57
	v_or_b32_e32 v37, s25, v88
	v_cndmask_b32_e32 v38, v231, v38, vcc
	v_cmp_gt_u32_e32 vcc, s17, v37
	s_waitcnt lgkmcnt(0)
	v_add_f32_e32 v43, v44, v100
	v_cndmask_b32_e32 v37, v231, v40, vcc
	v_or_b32_e32 v40, s25, v89
	v_cmp_gt_u32_e32 vcc, s17, v40
	v_or_b32_e32 v40, s25, v93
	v_add_f32_e32 v44, v45, v101
	v_cndmask_b32_e32 v41, v231, v41, vcc
	v_cmp_gt_u32_e32 vcc, s17, v40
	ds_read2_b32 v[100:101], v102 offset0:58 offset1:59
	v_max3_f32 v99, v99, v38, v37
	v_cndmask_b32_e32 v40, v231, v42, vcc
	v_or_b32_e32 v42, s25, v94
	v_cmp_gt_u32_e32 vcc, s17, v42
	v_or_b32_e32 v42, s25, v95
	s_waitcnt lgkmcnt(0)
	v_add_f32_e32 v45, v46, v100
	v_cndmask_b32_e32 v43, v231, v43, vcc
	v_cmp_gt_u32_e32 vcc, s17, v42
	v_add_f32_e32 v46, v47, v101
	v_or_b32_e32 v100, s2, v82
	v_cndmask_b32_e32 v42, v231, v44, vcc
	v_or_b32_e32 v44, s25, v96
	v_cmp_gt_u32_e32 vcc, s17, v44
	v_or_b32_e32 v44, s25, v97
	v_max3_f32 v99, v99, v41, v40
	v_cndmask_b32_e32 v45, v231, v45, vcc
	v_cmp_gt_u32_e32 vcc, s17, v44
	v_max3_f32 v99, v99, v43, v42
	v_or_b32_e32 v82, s1, v82
	v_cndmask_b32_e32 v44, v231, v46, vcc
	v_sub_u32_e32 v46, 0x60, v240
	v_lshlrev_b32_e32 v101, 2, v46
	v_add_u32_e32 v46, v83, v101
	ds_read2_b32 v[46:47], v46 offset0:32 offset1:33
	v_cmp_gt_u32_e32 vcc, s17, v100
	v_add3_u32 v102, s0, v101, v220
	v_or_b32_e32 v100, s2, v86
	v_max3_f32 v99, v99, v45, v44
	s_waitcnt lgkmcnt(0)
	v_add_f32_e32 v16, v16, v46
	v_or_b32_e32 v46, s2, v85
	v_cndmask_b32_e32 v16, v231, v16, vcc
	v_add_f32_e32 v17, v17, v47
	v_cmp_gt_u32_e32 vcc, s17, v46
	ds_read2_b32 v[46:47], v102 offset0:34 offset1:35
	s_nop 0
	v_cndmask_b32_e32 v17, v231, v17, vcc
	v_cmp_gt_u32_e32 vcc, s17, v100
	ds_read2_b32 v[100:101], v102 offset0:40 offset1:41
	s_waitcnt lgkmcnt(0)
	v_add_f32_e32 v18, v18, v46
	v_cndmask_b32_e32 v46, v231, v18, vcc
	v_or_b32_e32 v18, s2, v87
	v_add_f32_e32 v19, v19, v47
	v_add_f32_e32 v20, v20, v100
	v_add_f32_e32 v21, v21, v101
	ds_read2_b32 v[100:101], v102 offset0:42 offset1:43
	v_cmp_gt_u32_e32 vcc, s17, v18
	v_max3_f32 v99, v99, v16, v17
	s_waitcnt lgkmcnt(0)
	v_add_f32_e32 v22, v22, v100
	v_cndmask_b32_e32 v18, v231, v19, vcc
	v_or_b32_e32 v19, s2, v91
	v_cmp_gt_u32_e32 vcc, s17, v19
	v_or_b32_e32 v19, s2, v84
	v_add_f32_e32 v23, v23, v101
	v_cndmask_b32_e32 v20, v231, v20, vcc
	v_cmp_gt_u32_e32 vcc, s17, v19
	ds_read2_b32 v[100:101], v102 offset0:48 offset1:49
	v_max3_f32 v47, v99, v46, v18
	v_cndmask_b32_e32 v19, v231, v21, vcc
	v_max3_f32 v21, v47, v20, v19
	v_or_b32_e32 v47, s2, v92
	v_cmp_gt_u32_e32 vcc, s17, v47
	s_nop 1
	v_cndmask_b32_e32 v47, v231, v22, vcc
	v_or_b32_e32 v22, s2, v81
	v_cmp_gt_u32_e32 vcc, s17, v22
	s_waitcnt lgkmcnt(0)
	v_add_f32_e32 v22, v24, v100
	v_add_f32_e32 v24, v25, v101
	ds_read2_b32 v[100:101], v102 offset0:50 offset1:51
	v_cndmask_b32_e32 v23, v231, v23, vcc
	v_max3_f32 v99, v21, v47, v23
	v_or_b32_e32 v21, s2, v90
	v_cmp_gt_u32_e32 vcc, s17, v21
	s_waitcnt lgkmcnt(0)
	v_add_f32_e32 v25, v26, v100
	v_add_f32_e32 v26, v27, v101
	ds_read2_b32 v[100:101], v102 offset0:56 offset1:57
	v_or_b32_e32 v21, s2, v88
	v_cndmask_b32_e32 v22, v231, v22, vcc
	v_cmp_gt_u32_e32 vcc, s17, v21
	s_waitcnt lgkmcnt(0)
	v_add_f32_e32 v27, v28, v100
	v_cndmask_b32_e32 v21, v231, v24, vcc
	v_or_b32_e32 v24, s2, v89
	v_cmp_gt_u32_e32 vcc, s17, v24
	v_or_b32_e32 v24, s2, v93
	v_add_f32_e32 v28, v29, v101
	v_cndmask_b32_e32 v25, v231, v25, vcc
	v_cmp_gt_u32_e32 vcc, s17, v24
	ds_read2_b32 v[100:101], v102 offset0:58 offset1:59
	v_max3_f32 v99, v99, v22, v21
	v_cndmask_b32_e32 v24, v231, v26, vcc
	v_or_b32_e32 v26, s2, v94
	v_cmp_gt_u32_e32 vcc, s17, v26
	v_or_b32_e32 v26, s2, v95
	s_waitcnt lgkmcnt(0)
	v_add_f32_e32 v29, v30, v100
	v_cndmask_b32_e32 v27, v231, v27, vcc
	v_cmp_gt_u32_e32 vcc, s17, v26
	v_add_f32_e32 v30, v31, v101
	v_max3_f32 v99, v99, v25, v24
	v_cndmask_b32_e32 v26, v231, v28, vcc
	v_or_b32_e32 v28, s2, v96
	v_cmp_gt_u32_e32 vcc, s17, v28
	v_or_b32_e32 v28, s2, v97
	v_max3_f32 v99, v99, v27, v26
	v_cndmask_b32_e32 v29, v231, v29, vcc
	v_cmp_gt_u32_e32 vcc, s17, v28
	s_nop 1
	v_cndmask_b32_e32 v28, v231, v30, vcc
	v_sub_u32_e32 v30, 0x80, v240
	v_lshlrev_b32_e32 v100, 2, v30
	v_add_u32_e32 v30, v83, v100
	ds_read2_b32 v[30:31], v30 offset0:32 offset1:33
	v_cmp_gt_u32_e32 vcc, s17, v82
	v_add3_u32 v100, s0, v100, v220
	v_or_b32_e32 v83, s1, v86
	v_max3_f32 v99, v99, v29, v28
	s_waitcnt lgkmcnt(0)
	v_add_f32_e32 v0, v0, v30
	v_or_b32_e32 v30, s1, v85
	v_cndmask_b32_e32 v0, v231, v0, vcc
	v_add_f32_e32 v1, v1, v31
	v_cmp_gt_u32_e32 vcc, s17, v30
	ds_read2_b32 v[30:31], v100 offset0:34 offset1:35
	s_waitcnt lgkmcnt(0)
; __device__ __forceinline__ float shx(float v, int lane, int mask) { return __builtin_bit_cast(float, __builtin_amdgcn_ds_bpermute((lane ^ mask) << 2, __builtin_bit_cast(int, v))); }
; __device__ __forceinline__ void dil_unit(LAS unsigned char* lds, const LAS float* btab, const bf16_t* QKV, int gi, int ldil, int b, int h, int r, int ub, bf16_t* AO, float* lseacc, const int tid) {
;     ...
;         for (int rr = 0; rr < 16; ++rr) { const int cr = (rr & 3) + 8 * (rr >> 2) + 4 * hi, jk = 32 * t + cr - r32, ki = k0 + 32 * wid + 32 * t + cr;
;             float s = S[t][rr] + btab[jk + 32];
;             s = ((unsigned)ki < (unsigned)sub_len) ? s : -1e30f;
;             S[t][rr] = s; m = fmaxf(m, s); }
;     m = fmaxf(m, pg8::shx(m, lane, 32));
;     float l = 0.f;
; #pragma unroll
;     for (int t = 0; t < 5; ++t)
; #pragma unroll
;         for (int rr = 0; rr < 16; ++rr) { const float p = __builtin_amdgcn_exp2f(S[t][rr] - m); S[t][rr] = p; l += p; }
	v_add_f32_e32 v2, v2, v30
	v_cndmask_b32_e32 v1, v231, v1, vcc
	v_cmp_gt_u32_e32 vcc, s17, v83
	v_add_f32_e32 v3, v3, v31
	v_max3_f32 v82, v99, v0, v1
	v_cndmask_b32_e32 v30, v231, v2, vcc
	v_or_b32_e32 v2, s1, v87
	v_cmp_gt_u32_e32 vcc, s17, v2
	s_nop 1
	v_cndmask_b32_e32 v2, v231, v3, vcc
	v_max3_f32 v31, v82, v30, v2
	ds_read2_b32 v[82:83], v100 offset0:40 offset1:41
	v_or_b32_e32 v3, s1, v91
	v_cmp_gt_u32_e32 vcc, s17, v3
	v_or_b32_e32 v3, s1, v84
	ds_read2_b32 v[84:85], v100 offset0:48 offset1:49
	s_waitcnt lgkmcnt(0)
	v_add_f32_e32 v4, v4, v82
	v_add_f32_e32 v5, v5, v83
	ds_read2_b32 v[82:83], v100 offset0:42 offset1:43
	v_cndmask_b32_e32 v4, v231, v4, vcc
	v_cmp_gt_u32_e32 vcc, s17, v3
	s_waitcnt lgkmcnt(0)
	v_add_f32_e32 v6, v6, v82
	v_cndmask_b32_e32 v3, v231, v5, vcc
	v_max3_f32 v5, v31, v4, v3
	v_or_b32_e32 v31, s1, v92
	v_cmp_gt_u32_e32 vcc, s17, v31
	v_add_f32_e32 v7, v7, v83
	s_nop 0
	v_cndmask_b32_e32 v82, v231, v6, vcc
	v_or_b32_e32 v6, s1, v81
	v_cmp_gt_u32_e32 vcc, s17, v6
	v_or_b32_e32 v6, s1, v90
	v_or_b32_e32 v81, s1, v96
	v_cndmask_b32_e32 v31, v231, v7, vcc
	v_add_f32_e32 v7, v8, v84
	v_add_f32_e32 v8, v9, v85
	ds_read2_b32 v[84:85], v100 offset0:50 offset1:51
	v_cmp_gt_u32_e32 vcc, s17, v6
	v_or_b32_e32 v6, s1, v88
	v_max3_f32 v5, v5, v82, v31
	v_cndmask_b32_e32 v7, v231, v7, vcc
	v_cmp_gt_u32_e32 vcc, s17, v6
	s_waitcnt lgkmcnt(0)
	v_add_f32_e32 v9, v10, v84
	v_add_f32_e32 v10, v11, v85
	ds_read2_b32 v[84:85], v100 offset0:56 offset1:57
	v_cndmask_b32_e32 v6, v231, v8, vcc
	v_or_b32_e32 v8, s1, v89
	v_cmp_gt_u32_e32 vcc, s17, v8
	v_or_b32_e32 v8, s1, v93
	s_waitcnt lgkmcnt(0)
	v_add_f32_e32 v11, v12, v84
	v_cndmask_b32_e32 v9, v231, v9, vcc
	v_cmp_gt_u32_e32 vcc, s17, v8
	v_add_f32_e32 v12, v13, v85
	v_max3_f32 v5, v5, v7, v6
	v_cndmask_b32_e32 v8, v231, v10, vcc
	v_or_b32_e32 v10, s1, v94
	v_cmp_gt_u32_e32 vcc, s17, v10
	v_or_b32_e32 v10, s1, v95
	v_max3_f32 v5, v5, v9, v8
	v_cndmask_b32_e32 v11, v231, v11, vcc
	v_cmp_gt_u32_e32 vcc, s17, v10
	s_nop 1
	v_cndmask_b32_e32 v10, v231, v12, vcc
	ds_read2_b32 v[12:13], v100 offset0:58 offset1:59
	v_cmp_gt_u32_e32 vcc, s17, v81
	v_max3_f32 v5, v5, v11, v10
	s_waitcnt lgkmcnt(0)
	v_add_f32_e32 v12, v14, v12
	v_cndmask_b32_e32 v81, v231, v12, vcc
	v_or_b32_e32 v12, s1, v97
	v_add_f32_e32 v13, v15, v13
	v_cmp_gt_u32_e32 vcc, s17, v12
	v_lshlrev_b32_e32 v12, 2, v238
	v_xor_b32_e32 v12, 0x80, v12
	v_cndmask_b32_e32 v15, v231, v13, vcc
	v_max3_f32 v5, v5, v81, v15
	ds_bpermute_b32 v13, v12, v5
	s_and_b64 vcc, exec, s[10:11]
	s_waitcnt lgkmcnt(0)
	v_max_f32_e32 v13, v13, v13
	v_max_f32_e32 v5, v5, v13
	v_sub_f32_e32 v13, v64, v5
	v_exp_f32_e32 v13, v13
	v_sub_f32_e32 v14, v65, v5
	v_exp_f32_e32 v14, v14
	v_sub_f32_e32 v73, v73, v5
	v_add_f32_e32 v64, 0, v13
	v_exp_f32_e32 v73, v73
	v_add_f32_e32 v65, v14, v64
	v_sub_f32_e32 v64, v66, v5
	v_exp_f32_e32 v64, v64
	v_sub_f32_e32 v75, v75, v5
	v_exp_f32_e32 v75, v75
	v_sub_f32_e32 v48, v48, v5
	v_add_f32_e32 v66, v64, v65
	v_sub_f32_e32 v65, v67, v5
	v_exp_f32_e32 v65, v65
	v_exp_f32_e32 v48, v48
	v_sub_f32_e32 v49, v49, v5
	v_exp_f32_e32 v49, v49
	v_add_f32_e32 v67, v65, v66
	v_sub_f32_e32 v66, v68, v5
	v_exp_f32_e32 v66, v66
	v_sub_f32_e32 v50, v50, v5
	v_exp_f32_e32 v50, v50
	v_sub_f32_e32 v52, v52, v5
	v_add_f32_e32 v68, v66, v67
	v_sub_f32_e32 v67, v69, v5
	v_exp_f32_e32 v67, v67
	v_sub_f32_e32 v51, v51, v5
	v_exp_f32_e32 v51, v51
	v_sub_f32_e32 v55, v55, v5
	v_add_f32_e32 v69, v67, v68
	v_sub_f32_e32 v68, v70, v5
	v_exp_f32_e32 v68, v68
	v_exp_f32_e32 v55, v55
	v_sub_f32_e32 v54, v54, v5
	v_exp_f32_e32 v83, v54
	v_add_f32_e32 v70, v68, v69
	v_sub_f32_e32 v69, v71, v5
	v_exp_f32_e32 v69, v69
	v_sub_f32_e32 v53, v53, v5
	v_exp_f32_e32 v84, v53
	v_sub_f32_e32 v53, v57, v5
	v_add_f32_e32 v71, v69, v70
	v_sub_f32_e32 v70, v80, v5
	v_exp_f32_e32 v70, v70
	v_exp_f32_e32 v85, v53
	v_sub_f32_e32 v53, v56, v5
	v_exp_f32_e32 v86, v53
	v_add_f32_e32 v80, v70, v71
	v_sub_f32_e32 v71, v72, v5
	v_exp_f32_e32 v71, v71
	v_sub_f32_e32 v72, v74, v5
	v_exp_f32_e32 v72, v72
	v_sub_f32_e32 v53, v59, v5
	v_add_f32_e32 v80, v71, v80
	v_exp_f32_e32 v87, v53
	v_add_f32_e32 v74, v72, v80
	v_add_f32_e32 v80, v73, v74
	v_sub_f32_e32 v74, v76, v5
	v_exp_f32_e32 v74, v74
	v_sub_f32_e32 v53, v58, v5
	v_exp_f32_e32 v88, v53
	v_sub_f32_e32 v53, v60, v5
	v_add_f32_e32 v76, v74, v80
	v_add_f32_e32 v80, v75, v76
	v_sub_f32_e32 v76, v77, v5
	v_exp_f32_e32 v76, v76
	v_sub_f32_e32 v77, v78, v5
	v_exp_f32_e32 v77, v77
	v_exp_f32_e32 v89, v53
	v_add_f32_e32 v80, v76, v80
	v_sub_f32_e32 v53, v61, v5
	v_add_f32_e32 v78, v77, v80
	v_add_f32_e32 v78, v48, v78
	v_add_f32_e32 v80, v49, v78
	v_sub_f32_e32 v78, v79, v5
	v_exp_f32_e32 v78, v78
	v_exp_f32_e32 v90, v53
	v_sub_f32_e32 v32, v32, v5
	v_exp_f32_e32 v32, v32
	v_add_f32_e32 v79, v78, v80
	v_add_f32_e32 v80, v50, v79
	v_exp_f32_e32 v79, v52
	v_sub_f32_e32 v33, v33, v5
	v_exp_f32_e32 v33, v33
	v_sub_f32_e32 v53, v62, v5
	v_add_f32_e32 v52, v79, v80
	v_sub_f32_e32 v80, v98, v5
	v_exp_f32_e32 v80, v80
	v_add_f32_e32 v52, v51, v52
	v_exp_f32_e32 v91, v53
	v_sub_f32_e32 v34, v34, v5
	v_add_f32_e32 v52, v80, v52
	v_add_f32_e32 v52, v55, v52
	v_add_f32_e32 v52, v83, v52
	v_add_f32_e32 v52, v84, v52
	v_add_f32_e32 v52, v85, v52
	v_add_f32_e32 v52, v86, v52
	v_add_f32_e32 v52, v87, v52
	v_add_f32_e32 v52, v88, v52
	v_add_f32_e32 v52, v89, v52
	v_add_f32_e32 v52, v90, v52
	v_exp_f32_e32 v34, v34
	v_sub_f32_e32 v36, v36, v5
	v_add_f32_e32 v52, v32, v52
	v_exp_f32_e32 v36, v36
	v_sub_f32_e32 v35, v35, v5
	v_add_f32_e32 v52, v33, v52
	v_exp_f32_e32 v35, v35
	v_sub_f32_e32 v53, v63, v5
	v_add_f32_e32 v52, v91, v52
; __device__ __forceinline__ float shx(float v, int lane, int mask) { return __builtin_bit_cast(float, __builtin_amdgcn_ds_bpermute((lane ^ mask) << 2, __builtin_bit_cast(int, v))); }
; __device__ __forceinline__ void dil_unit(LAS unsigned char* lds, const LAS float* btab, const bf16_t* QKV, int gi, int ldil, int b, int h, int r, int ub, bf16_t* AO, float* lseacc, const int tid) {
;     ...
;         for (int rr = 0; rr < 16; ++rr) { const float p = __builtin_amdgcn_exp2f(S[t][rr] - m); S[t][rr] = p; l += p; }
;     l += pg8::shx(l, lane, 32);
;     const float inv = __builtin_amdgcn_rcpf(l), lse = m + __builtin_amdgcn_logf(l);
;     bf16x8 pf[10];
; #pragma unroll
;     for (int t = 0; t < 5; ++t) { pf[2 * t] = pack8(S[t], 0); pf[2 * t + 1] = pack8(S[t], 8); }
;     bf16_t* orow = AO + qtok * 1024 + h * 128;
;     u32x4 oldv[4][2] = {};
;     if (gi > 0) {
; #pragma unroll
;         for (int d0 = 0; d0 < 4; ++d0)
; #pragma unroll
;             for (int g2 = 0; g2 < 2; ++g2) oldv[d0][g2] = *(const u32x4*)(orow + 32 * d0 + 16 * g2 + (hi ? 8 : 0)); }
	v_exp_f32_e32 v92, v53
	v_sub_f32_e32 v39, v39, v5
	v_add_f32_e32 v52, v34, v52
	v_exp_f32_e32 v39, v39
	v_sub_f32_e32 v38, v38, v5
	v_add_f32_e32 v52, v36, v52
	v_exp_f32_e32 v38, v38
	v_sub_f32_e32 v37, v37, v5
	v_add_f32_e32 v52, v35, v52
	v_exp_f32_e32 v37, v37
	v_sub_f32_e32 v41, v41, v5
	v_add_f32_e32 v52, v92, v52
	v_exp_f32_e32 v41, v41
	v_sub_f32_e32 v40, v40, v5
	v_add_f32_e32 v52, v39, v52
	v_exp_f32_e32 v93, v40
	v_sub_f32_e32 v43, v43, v5
	v_add_f32_e32 v52, v38, v52
	v_exp_f32_e32 v43, v43
	v_sub_f32_e32 v42, v42, v5
	v_add_f32_e32 v52, v37, v52
	v_exp_f32_e32 v42, v42
	v_sub_f32_e32 v45, v45, v5
	v_add_f32_e32 v52, v41, v52
	v_exp_f32_e32 v94, v45
	v_sub_f32_e32 v44, v44, v5
	v_add_f32_e32 v40, v93, v52
	v_exp_f32_e32 v95, v44
	v_sub_f32_e32 v16, v16, v5
	v_add_f32_e32 v40, v43, v40
	v_exp_f32_e32 v16, v16
	v_sub_f32_e32 v17, v17, v5
	v_add_f32_e32 v40, v42, v40
	v_exp_f32_e32 v17, v17
	v_sub_f32_e32 v44, v46, v5
	v_add_f32_e32 v40, v94, v40
	v_exp_f32_e32 v96, v44
	v_sub_f32_e32 v18, v18, v5
	v_add_f32_e32 v40, v95, v40
	v_exp_f32_e32 v18, v18
	v_sub_f32_e32 v20, v20, v5
	v_add_f32_e32 v40, v16, v40
	v_exp_f32_e32 v20, v20
	v_sub_f32_e32 v19, v19, v5
	v_add_f32_e32 v40, v17, v40
	v_exp_f32_e32 v19, v19
	v_sub_f32_e32 v44, v47, v5
	v_add_f32_e32 v40, v96, v40
	v_exp_f32_e32 v97, v44
	v_sub_f32_e32 v23, v23, v5
	v_add_f32_e32 v40, v18, v40
	v_exp_f32_e32 v23, v23
	v_sub_f32_e32 v22, v22, v5
	v_add_f32_e32 v40, v20, v40
	v_exp_f32_e32 v22, v22
	v_sub_f32_e32 v21, v21, v5
	v_add_f32_e32 v40, v19, v40
	v_exp_f32_e32 v21, v21
	v_sub_f32_e32 v25, v25, v5
	v_add_f32_e32 v40, v97, v40
	v_exp_f32_e32 v25, v25
	v_sub_f32_e32 v24, v24, v5
	v_add_f32_e32 v40, v23, v40
	v_exp_f32_e32 v24, v24
	v_sub_f32_e32 v27, v27, v5
	v_add_f32_e32 v40, v22, v40
	v_exp_f32_e32 v27, v27
	v_sub_f32_e32 v26, v26, v5
	v_add_f32_e32 v40, v21, v40
	v_exp_f32_e32 v26, v26
	v_sub_f32_e32 v29, v29, v5
	v_add_f32_e32 v40, v25, v40
	v_exp_f32_e32 v29, v29
	v_sub_f32_e32 v28, v28, v5
	v_add_f32_e32 v40, v24, v40
	v_exp_f32_e32 v28, v28
	v_sub_f32_e32 v0, v0, v5
	v_add_f32_e32 v40, v27, v40
	v_exp_f32_e32 v0, v0
	v_sub_f32_e32 v1, v1, v5
	v_add_f32_e32 v40, v26, v40
	v_exp_f32_e32 v1, v1
	v_sub_f32_e32 v30, v30, v5
	v_add_f32_e32 v40, v29, v40
	v_exp_f32_e32 v30, v30
	v_sub_f32_e32 v2, v2, v5
	v_add_f32_e32 v40, v28, v40
	v_exp_f32_e32 v98, v2
	v_sub_f32_e32 v4, v4, v5
	v_add_f32_e32 v40, v0, v40
	v_exp_f32_e32 v4, v4
	v_sub_f32_e32 v3, v3, v5
	v_add_f32_e32 v40, v1, v40
	v_exp_f32_e32 v99, v3
	v_sub_f32_e32 v3, v82, v5
	v_add_f32_e32 v40, v30, v40
	v_exp_f32_e32 v82, v3
	v_sub_f32_e32 v3, v31, v5
	v_add_f32_e32 v2, v98, v40
	v_exp_f32_e32 v31, v3
	v_sub_f32_e32 v3, v7, v5
	v_add_f32_e32 v2, v4, v2
	v_exp_f32_e32 v7, v3
	v_sub_f32_e32 v3, v6, v5
	v_add_f32_e32 v2, v99, v2
	v_exp_f32_e32 v6, v3
	v_sub_f32_e32 v3, v9, v5
	v_add_f32_e32 v2, v82, v2
	v_exp_f32_e32 v9, v3
	v_sub_f32_e32 v3, v8, v5
	v_add_f32_e32 v2, v31, v2
	v_exp_f32_e32 v8, v3
	v_sub_f32_e32 v3, v11, v5
	v_add_f32_e32 v2, v7, v2
	v_exp_f32_e32 v11, v3
	v_sub_f32_e32 v3, v10, v5
	v_add_f32_e32 v2, v6, v2
	v_exp_f32_e32 v10, v3
	v_sub_f32_e32 v3, v81, v5
	v_add_f32_e32 v2, v9, v2
	v_exp_f32_e32 v81, v3
	v_sub_f32_e32 v3, v15, v5
	v_add_f32_e32 v2, v8, v2
	v_exp_f32_e32 v15, v3
	v_add_f32_e32 v2, v11, v2
	v_add_f32_e32 v2, v10, v2
	v_add_f32_e32 v2, v81, v2
	v_add_f32_e32 v2, v15, v2
	ds_bpermute_b32 v3, v12, v2
	v_cvt_pk_bf16_f32 v60, v13, v14
	v_cvt_pk_bf16_f32 v61, v64, v65
	v_cvt_pk_bf16_f32 v62, v66, v67
	v_cvt_pk_bf16_f32 v63, v68, v69
	v_cvt_pk_bf16_f32 v56, v70, v71
	v_cvt_pk_bf16_f32 v57, v72, v73
	v_cvt_pk_bf16_f32 v58, v74, v75
	v_cvt_pk_bf16_f32 v59, v76, v77
	v_cvt_pk_bf16_f32 v52, v48, v49
	v_cvt_pk_bf16_f32 v53, v78, v50
	v_cvt_pk_bf16_f32 v54, v79, v51
	v_cvt_pk_bf16_f32 v55, v80, v55
	v_cvt_pk_bf16_f32 v48, v83, v84
	v_cvt_pk_bf16_f32 v49, v85, v86
	v_cvt_pk_bf16_f32 v50, v87, v88
	v_cvt_pk_bf16_f32 v51, v89, v90
	v_cvt_pk_bf16_f32 v44, v32, v33
	v_cvt_pk_bf16_f32 v45, v91, v34
	v_cvt_pk_bf16_f32 v46, v36, v35
	v_cvt_pk_bf16_f32 v47, v92, v39
	v_cvt_pk_bf16_f32 v40, v38, v37
	v_cvt_pk_bf16_f32 v41, v41, v93
	v_cvt_pk_bf16_f32 v42, v43, v42
	v_cvt_pk_bf16_f32 v43, v94, v95
	v_cvt_pk_bf16_f32 v36, v16, v17
	v_cvt_pk_bf16_f32 v37, v96, v18
	v_cvt_pk_bf16_f32 v38, v20, v19
	v_cvt_pk_bf16_f32 v39, v97, v23
	v_cvt_pk_bf16_f32 v32, v22, v21
	v_cvt_pk_bf16_f32 v33, v25, v24
	v_cvt_pk_bf16_f32 v34, v27, v26
	v_cvt_pk_bf16_f32 v35, v29, v28
	v_cvt_pk_bf16_f32 v28, v0, v1
	v_lshlrev_b64 v[0:1], 11, v[218:219]
	v_lshl_add_u64 v[0:1], s[6:7], 0, v[0:1]
	v_cvt_pk_bf16_f32 v29, v30, v98
	v_cvt_pk_bf16_f32 v30, v4, v99
	v_cvt_pk_bf16_f32 v31, v82, v31
	v_cvt_pk_bf16_f32 v24, v7, v6
	v_cvt_pk_bf16_f32 v25, v9, v8
	v_cvt_pk_bf16_f32 v26, v11, v10
	v_cvt_pk_bf16_f32 v27, v81, v15
	v_lshl_add_u64 v[0:1], v[0:1], 0, s[96:97]
	v_mov_b32_e32 v88, 0
	v_mov_b32_e32 v16, 0
	v_mov_b32_e32 v17, 0
	v_mov_b32_e32 v18, 0
	v_mov_b32_e32 v19, 0
	v_mov_b32_e32 v20, 0
	v_mov_b32_e32 v21, 0
	v_mov_b32_e32 v22, 0
	v_mov_b32_e32 v23, 0
	v_mov_b32_e32 v64, 0
	v_mov_b32_e32 v65, 0
	v_mov_b32_e32 v66, 0
	v_mov_b32_e32 v67, 0
	v_mov_b32_e32 v68, 0
	v_mov_b32_e32 v69, 0
	v_mov_b32_e32 v70, 0
	v_mov_b32_e32 v71, 0
	v_mov_b32_e32 v72, 0
	v_mov_b32_e32 v73, 0
	v_mov_b32_e32 v74, 0
	v_mov_b32_e32 v75, 0
	v_mov_b32_e32 v76, 0
	v_mov_b32_e32 v77, 0
	v_mov_b32_e32 v78, 0
	v_mov_b32_e32 v79, 0
	v_mov_b32_e32 v80, 0
	v_mov_b32_e32 v81, 0
	v_mov_b32_e32 v82, 0
	v_mov_b32_e32 v83, 0
	v_mov_b32_e32 v84, 0
	v_mov_b32_e32 v85, 0
	v_mov_b32_e32 v86, 0
	v_mov_b32_e32 v87, 0
	s_cbranch_vccz .LBB0_668
	v_and_b32_e32 v4, 8, v221
	v_lshlrev_b32_e32 v208, 1, v4
	v_lshl_add_u64 v[6:7], v[0:1], 0, v[208:209]
	global_load_dwordx4 v[84:87], v[6:7], off
	global_load_dwordx4 v[80:83], v[6:7], off offset:32
	global_load_dwordx4 v[76:79], v[6:7], off offset:64
	global_load_dwordx4 v[72:75], v[6:7], off offset:96
	global_load_dwordx4 v[68:71], v[6:7], off offset:128
	global_load_dwordx4 v[64:67], v[6:7], off offset:160
	global_load_dwordx4 v[20:23], v[6:7], off offset:192
	global_load_dwordx4 v[16:19], v[6:7], off offset:224
